# dilated attention: the 9 Oacc/Lacc read-modify-write loads issued together (one round trip instead of two)
# speedup vs baseline: 1.0113x; 1.0113x over previous
.LBB0_235:
	ds_bpermute_b32 v1, v242, v245
	v_ashrrev_i32_e32 v197, 31, v196
	v_lshlrev_b64 v[2:3], 10, v[196:197]
	s_andn2_b64 vcc, exec, s[46:47]
	v_lshl_add_u64 v[2:3], v[144:145], 0, v[2:3]
	s_waitcnt lgkmcnt(0)
	v_add_f32_e32 v1, v245, v1
	s_cbranch_vccnz .LBB0_238
	global_load_dwordx4 v[4:7], v[2:3], off
	global_load_dwordx4 v[8:11], v[2:3], off offset:32
	global_load_dwordx4 v[12:15], v[2:3], off offset:64
	global_load_dwordx4 v[48:51], v[2:3], off offset:96
	global_load_dwordx4 v[64:67], v[2:3], off offset:128
	global_load_dwordx4 v[68:71], v[2:3], off offset:160
	global_load_dwordx4 v[72:75], v[2:3], off offset:192
	global_load_dwordx4 v[76:79], v[2:3], off offset:224
	v_lshl_add_u64 v[80:81], v[196:197], 4, s[0:1]
	global_load_dword v80, v[80:81], off
	s_waitcnt vmcnt(8)
	v_pk_add_f32 v[34:35], v[34:35], v[6:7]
	v_pk_add_f32 v[32:33], v[32:33], v[4:5]
	s_waitcnt vmcnt(7)
	v_pk_add_f32 v[38:39], v[38:39], v[10:11]
	v_pk_add_f32 v[36:37], v[36:37], v[8:9]
	s_waitcnt vmcnt(6)
	v_pk_add_f32 v[42:43], v[42:43], v[14:15]
	v_pk_add_f32 v[40:41], v[40:41], v[12:13]
	s_waitcnt vmcnt(5)
	v_pk_add_f32 v[46:47], v[46:47], v[50:51]
	v_pk_add_f32 v[44:45], v[44:45], v[48:49]
	s_waitcnt vmcnt(4)
	v_pk_add_f32 v[16:17], v[16:17], v[64:65]
	v_pk_add_f32 v[18:19], v[18:19], v[66:67]
	s_waitcnt vmcnt(3)
	v_pk_add_f32 v[20:21], v[20:21], v[68:69]
	v_pk_add_f32 v[22:23], v[22:23], v[70:71]
	s_waitcnt vmcnt(2)
	v_pk_add_f32 v[24:25], v[24:25], v[72:73]
	v_pk_add_f32 v[26:27], v[26:27], v[74:75]
	s_waitcnt vmcnt(1)
	v_pk_add_f32 v[28:29], v[28:29], v[76:77]
	v_pk_add_f32 v[30:31], v[30:31], v[78:79]
	s_waitcnt vmcnt(0)
	v_add_f32_e32 v1, v1, v80
	s_andn2_b64 vcc, exec, s[14:15]
	s_mov_b64 s[20:21], -1
	s_cbranch_vccz .LBB0_239
